# final RMSNorm phase: software-pipelined loads, DPP row reduction + 2 bpermutes, loads drained at loop exit
# speedup vs baseline: 1.0036x; 1.0014x over previous
; __device__ __forceinline__ int obid() { int t = blockIdx.x; asm volatile("" : "+s"(t)); return t; }
; __device__ void phase_final(const bf16_t* __restrict__ xr, const float* __restrict__ g, float* __restrict__ outf) {
;     ...
;     for (int row0 = obid() * 8 + wid; row0 < 65536; row0 += nb8 * 2) { const int row1 = row0 + nb8; const bool has1 = row1 < 65536;
;         const uint4 a0 = *(const uint4*)(xr + (size_t)row0 * 1024 + lane * 16), a1 = *(const uint4*)(xr + (size_t)row0 * 1024 + lane * 16 + 8);
;         const uint4 b0 = *(const uint4*)(xr + (size_t)(has1 ? row1 : row0) * 1024 + lane * 16), b1 = *(const uint4*)(xr + (size_t)(has1 ? row1 : row0) * 1024 + lane * 16 + 8);
.LBB0_234:
	v_readfirstlane_b32 s22, v56
	s_mov_b32 s31, 0
	s_add_i32 s23, s22, s11
	s_cmp_lt_i32 s23, s54
	s_cselect_b32 s24, s23, s22
	s_lshl_b32 s30, s22, 11
	v_lshl_add_u64 v[104:105], s[30:31], 0, v[16:17]
	s_lshl_b32 s30, s24, 11
	v_lshl_add_u64 v[106:107], s[30:31], 0, v[16:17]
	global_load_dwordx4 v[20:23], v[104:105], off
	global_load_dwordx4 v[24:27], v[104:105], off offset:16
	global_load_dwordx4 v[28:31], v[106:107], off
	global_load_dwordx4 v[32:35], v[106:107], off offset:16
	s_waitcnt vmcnt(0)
	s_branch .Lfin_body
.Lfin_loop:
	s_waitcnt vmcnt(8)
; __device__ __forceinline__ int obid() { int t = blockIdx.x; asm volatile("" : "+s"(t)); return t; }
; __device__ __forceinline__ float bflo(unsigned w) { return __uint_as_float(w << 16); }
; __device__ __forceinline__ float bfhi(unsigned w) { return __uint_as_float(w & 0xffff0000u); }
; __device__ void phase_final(const bf16_t* __restrict__ xr, const float* __restrict__ g, float* __restrict__ outf) {
;     ...
;     for (int row0 = obid() * 8 + wid; row0 < 65536; row0 += nb8 * 2) { const int row1 = row0 + nb8; const bool has1 = row1 < 65536;
;         const uint4 a0 = *(const uint4*)(xr + (size_t)row0 * 1024 + lane * 16), a1 = *(const uint4*)(xr + (size_t)row0 * 1024 + lane * 16 + 8);
;         const uint4 b0 = *(const uint4*)(xr + (size_t)(has1 ? row1 : row0) * 1024 + lane * 16), b1 = *(const uint4*)(xr + (size_t)(has1 ? row1 : row0) * 1024 + lane * 16 + 8);
;         f32x4 v[4] = {(f32x4){bflo(a0.x), bfhi(a0.x), bflo(a0.y), bfhi(a0.y)}, (f32x4){bflo(a0.z), bfhi(a0.z), bflo(a0.w), bfhi(a0.w)}, (f32x4){bflo(a1.x), bfhi(a1.x), bflo(a1.y), bfhi(a1.y)}, (f32x4){bflo(a1.z), bfhi(a1.z), bflo(a1.w), bfhi(a1.w)}};
;         f32x4 w[4] = {(f32x4){bflo(b0.x), bfhi(b0.x), bflo(b0.y), bfhi(b0.y)}, (f32x4){bflo(b0.z), bfhi(b0.z), bflo(b0.w), bfhi(b0.w)}, (f32x4){bflo(b1.x), bfhi(b1.x), bflo(b1.y), bfhi(b1.y)}, (f32x4){bflo(b1.z), bfhi(b1.z), bflo(b1.w), bfhi(b1.w)}};
;         float ss = 0.f, st = 0.f;
; #pragma unroll
;         for (int i = 0; i < 4; ++i) { ss += v[i][0] * v[i][0] + v[i][1] * v[i][1] + v[i][2] * v[i][2] + v[i][3] * v[i][3]; st += w[i][0] * w[i][0] + w[i][1] * w[i][1] + w[i][2] * w[i][2] + w[i][3] * w[i][3]; }
; #pragma unroll
;         for (int o = 32; o > 0; o >>= 1) { ss += __shfl_xor(ss, o); st += __shfl_xor(st, o); }
;         const float r0 = rsqrtf(ss * (1.0f / 1024.0f) + 1e-6f), r1 = rsqrtf(st * (1.0f / 1024.0f) + 1e-6f);
; #pragma unroll
;         for (int i = 0; i < 4; ++i) *(f32x4*)(outf + (size_t)row0 * 1024 + lane * 16 + i * 4) = v[i] * r0 * gv[i];
;         if (has1) {
; #pragma unroll
;             for (int i = 0; i < 4; ++i) *(f32x4*)(outf + (size_t)row1 * 1024 + lane * 16 + i * 4) = w[i] * r1 * gv[i]; }
;     }
.Lfin_body:
	v_lshlrev_b32_e32 v64, 16, v20
	v_and_b32_e32 v65, 0xffff0000, v20
	v_lshlrev_b32_e32 v66, 16, v21
	v_and_b32_e32 v67, 0xffff0000, v21
	v_lshlrev_b32_e32 v68, 16, v22
	v_and_b32_e32 v69, 0xffff0000, v22
	v_lshlrev_b32_e32 v70, 16, v23
	v_and_b32_e32 v71, 0xffff0000, v23
	v_lshlrev_b32_e32 v72, 16, v24
	v_and_b32_e32 v73, 0xffff0000, v24
	v_lshlrev_b32_e32 v74, 16, v25
	v_and_b32_e32 v75, 0xffff0000, v25
	v_lshlrev_b32_e32 v76, 16, v26
	v_and_b32_e32 v77, 0xffff0000, v26
	v_lshlrev_b32_e32 v78, 16, v27
	v_and_b32_e32 v79, 0xffff0000, v27
	v_lshlrev_b32_e32 v80, 16, v28
	v_and_b32_e32 v81, 0xffff0000, v28
	v_lshlrev_b32_e32 v82, 16, v29
	v_and_b32_e32 v83, 0xffff0000, v29
	v_lshlrev_b32_e32 v84, 16, v30
	v_and_b32_e32 v85, 0xffff0000, v30
	v_lshlrev_b32_e32 v86, 16, v31
	v_and_b32_e32 v87, 0xffff0000, v31
	v_lshlrev_b32_e32 v88, 16, v32
	v_and_b32_e32 v89, 0xffff0000, v32
	v_lshlrev_b32_e32 v90, 16, v33
	v_and_b32_e32 v91, 0xffff0000, v33
	v_lshlrev_b32_e32 v92, 16, v34
	v_and_b32_e32 v93, 0xffff0000, v34
	v_lshlrev_b32_e32 v94, 16, v35
	v_and_b32_e32 v95, 0xffff0000, v35
	s_add_i32 s25, s22, s11
	s_cmp_lt_i32 s25, s54
	s_cselect_b64 s[40:41], -1, 0
	s_add_i32 s23, s25, s11
	s_cmp_lt_i32 s23, s54
	s_cselect_b32 s24, s23, s22
	s_add_i32 s25, s23, s11
	s_cmp_lt_i32 s25, s54
	s_cselect_b32 s25, s25, s24
	s_lshl_b32 s30, s24, 11
	v_lshl_add_u64 v[104:105], s[30:31], 0, v[16:17]
	s_lshl_b32 s30, s25, 11
	v_lshl_add_u64 v[106:107], s[30:31], 0, v[16:17]
	global_load_dwordx4 v[20:23], v[104:105], off
	global_load_dwordx4 v[24:27], v[104:105], off offset:16
	global_load_dwordx4 v[28:31], v[106:107], off
	global_load_dwordx4 v[32:35], v[106:107], off offset:16
	v_mul_f32_e32 v96, v64, v64
	v_mul_f32_e32 v97, v80, v80
	v_fmac_f32_e32 v96, v65, v65
	v_fmac_f32_e32 v97, v81, v81
	v_fmac_f32_e32 v96, v66, v66
	v_fmac_f32_e32 v97, v82, v82
	v_fmac_f32_e32 v96, v67, v67
	v_fmac_f32_e32 v97, v83, v83
	v_fmac_f32_e32 v96, v68, v68
	v_fmac_f32_e32 v97, v84, v84
	v_fmac_f32_e32 v96, v69, v69
	v_fmac_f32_e32 v97, v85, v85
	v_fmac_f32_e32 v96, v70, v70
	v_fmac_f32_e32 v97, v86, v86
	v_fmac_f32_e32 v96, v71, v71
	v_fmac_f32_e32 v97, v87, v87
	v_fmac_f32_e32 v96, v72, v72
	v_fmac_f32_e32 v97, v88, v88
	v_fmac_f32_e32 v96, v73, v73
	v_fmac_f32_e32 v97, v89, v89
	v_fmac_f32_e32 v96, v74, v74
	v_fmac_f32_e32 v97, v90, v90
	v_fmac_f32_e32 v96, v75, v75
	v_fmac_f32_e32 v97, v91, v91
	v_fmac_f32_e32 v96, v76, v76
	v_fmac_f32_e32 v97, v92, v92
	v_fmac_f32_e32 v96, v77, v77
	v_fmac_f32_e32 v97, v93, v93
	v_fmac_f32_e32 v96, v78, v78
	v_fmac_f32_e32 v97, v94, v94
	v_fmac_f32_e32 v96, v79, v79
	v_fmac_f32_e32 v97, v95, v95
	s_nop 1
	v_add_f32_dpp v96, v96, v96 quad_perm:[1,0,3,2] row_mask:0xf bank_mask:0xf
	v_add_f32_dpp v97, v97, v97 quad_perm:[1,0,3,2] row_mask:0xf bank_mask:0xf
	s_nop 1
	v_add_f32_dpp v96, v96, v96 quad_perm:[2,3,0,1] row_mask:0xf bank_mask:0xf
	v_add_f32_dpp v97, v97, v97 quad_perm:[2,3,0,1] row_mask:0xf bank_mask:0xf
	s_nop 1
	v_add_f32_dpp v96, v96, v96 row_half_mirror row_mask:0xf bank_mask:0xf
	v_add_f32_dpp v97, v97, v97 row_half_mirror row_mask:0xf bank_mask:0xf
	s_nop 1
	v_add_f32_dpp v96, v96, v96 row_mirror row_mask:0xf bank_mask:0xf
	v_add_f32_dpp v97, v97, v97 row_mirror row_mask:0xf bank_mask:0xf
	s_lshl_b32 s30, s22, 12
	v_lshl_add_u64 v[108:109], s[30:31], 0, v[18:19]
	s_add_i32 s24, s22, s11
	s_lshl_b32 s30, s24, 12
	v_lshl_add_u64 v[110:111], s[30:31], 0, v[18:19]
	ds_bpermute_b32 v98, v58, v96
	ds_bpermute_b32 v99, v58, v97
	s_waitcnt lgkmcnt(0)
	v_add_f32_e32 v96, v96, v98
	v_add_f32_e32 v97, v97, v99
	ds_bpermute_b32 v98, v41, v96
	ds_bpermute_b32 v99, v41, v97
	s_waitcnt lgkmcnt(0)
	v_add_f32_e32 v96, v96, v98
	v_add_f32_e32 v97, v97, v99
	v_mov_b32_e32 v98, 0x358637bd
	v_fmamk_f32 v96, v96, 0x3a800000, v98
	v_fmamk_f32 v97, v97, 0x3a800000, v98
	v_cmp_gt_f32_e64 s[24:25], s80, v96
	v_cmp_gt_f32_e32 vcc, s80, v97
	v_mul_f32_e32 v98, 0x4b800000, v96
	v_mul_f32_e32 v99, 0x4b800000, v97
	v_cndmask_b32_e64 v96, v96, v98, s[24:25]
	v_cndmask_b32_e32 v97, v97, v99, vcc
	v_rsq_f32_e32 v96, v96
	v_rsq_f32_e32 v97, v97
	s_nop 0
	v_mul_f32_e32 v98, 0x45800000, v96
	v_mul_f32_e32 v99, 0x45800000, v97
	v_cndmask_b32_e64 v100, v96, v98, s[24:25]
	v_cndmask_b32_e32 v102, v97, v99, vcc
	v_pk_mul_f32 v[64:65], v[100:101], v[64:65] op_sel_hi:[0,1]
	v_pk_mul_f32 v[66:67], v[100:101], v[66:67] op_sel_hi:[0,1]
	v_pk_mul_f32 v[64:65], v[12:13], v[64:65]
	v_pk_mul_f32 v[66:67], v[14:15], v[66:67]
	global_store_dwordx4 v[108:109], v[64:67], off
	v_pk_mul_f32 v[68:69], v[100:101], v[68:69] op_sel_hi:[0,1]
	v_pk_mul_f32 v[70:71], v[100:101], v[70:71] op_sel_hi:[0,1]
	v_pk_mul_f32 v[68:69], v[8:9], v[68:69]
	v_pk_mul_f32 v[70:71], v[10:11], v[70:71]
	global_store_dwordx4 v[108:109], v[68:71], off offset:16
	v_pk_mul_f32 v[72:73], v[100:101], v[72:73] op_sel_hi:[0,1]
	v_pk_mul_f32 v[74:75], v[100:101], v[74:75] op_sel_hi:[0,1]
	v_pk_mul_f32 v[72:73], v[4:5], v[72:73]
	v_pk_mul_f32 v[74:75], v[6:7], v[74:75]
	global_store_dwordx4 v[108:109], v[72:75], off offset:32
	v_pk_mul_f32 v[76:77], v[100:101], v[76:77] op_sel_hi:[0,1]
	v_pk_mul_f32 v[78:79], v[100:101], v[78:79] op_sel_hi:[0,1]
	v_pk_mul_f32 v[76:77], v[0:1], v[76:77]
	v_pk_mul_f32 v[78:79], v[2:3], v[78:79]
	global_store_dwordx4 v[108:109], v[76:79], off offset:48
	s_andn2_b64 vcc, exec, s[40:41]
	s_cbranch_vccnz .Lfin_exit
	v_pk_mul_f32 v[80:81], v[102:103], v[80:81] op_sel_hi:[0,1]
	v_pk_mul_f32 v[82:83], v[102:103], v[82:83] op_sel_hi:[0,1]
	v_pk_mul_f32 v[80:81], v[12:13], v[80:81]
	v_pk_mul_f32 v[82:83], v[14:15], v[82:83]
	global_store_dwordx4 v[110:111], v[80:83], off
	v_pk_mul_f32 v[84:85], v[102:103], v[84:85] op_sel_hi:[0,1]
	v_pk_mul_f32 v[86:87], v[102:103], v[86:87] op_sel_hi:[0,1]
	v_pk_mul_f32 v[84:85], v[8:9], v[84:85]
	v_pk_mul_f32 v[86:87], v[10:11], v[86:87]
	global_store_dwordx4 v[110:111], v[84:87], off offset:16
	v_pk_mul_f32 v[88:89], v[102:103], v[88:89] op_sel_hi:[0,1]
	v_pk_mul_f32 v[90:91], v[102:103], v[90:91] op_sel_hi:[0,1]
	v_pk_mul_f32 v[88:89], v[4:5], v[88:89]
	v_pk_mul_f32 v[90:91], v[6:7], v[90:91]
	global_store_dwordx4 v[110:111], v[88:91], off offset:32
	v_pk_mul_f32 v[92:93], v[102:103], v[92:93] op_sel_hi:[0,1]
	v_pk_mul_f32 v[94:95], v[102:103], v[94:95] op_sel_hi:[0,1]
	v_pk_mul_f32 v[92:93], v[0:1], v[92:93]
	v_pk_mul_f32 v[94:95], v[2:3], v[94:95]
	global_store_dwordx4 v[110:111], v[92:95], off offset:48
	s_cmp_lt_i32 s23, s54
	s_mov_b32 s22, s23
	s_cbranch_scc1 .Lfin_loop
.Lfin_exit:
	s_waitcnt vmcnt(0)
.LBB0_236:
	s_or_b64 exec, exec, s[20:21]
